# speedup vs baseline: 1.0090x; 1.0090x over previous
; __device__ __forceinline__ int otid() { int t; asm volatile("v_mov_b32 %0, %1" : "=v"(t) : "v"((int)threadIdx.x)); return t; }
; #define SETPTR(IT) { const int mt_ = ITEM_MT(IT), nt_ = ITEM_NT(IT); ga = A + (size_t)(mt_ * AROWS + srow) * lda + (skc ^ fs) * 8; gb = Bt + (size_t)(nt_ * 256 + srow) * ldb + (skc ^ fs) * 8; }
; #define ADV() { ga += 32; gb += 32; ck += 32; if (ck == K) { ck = 0; citem += gridDim.x; const int ci_ = citem < total ? citem : total - 1; SETPTR(ci_) } }
; #define WAITSTEP() { if (a2) WAITV(4); else WAITV(3); }
;     ...
;   const int tid = otid(), lane = tid & 63, wid = tid >> 6, wm = wid >> 2, wn = wid & 3, l15 = lane & 15, quad = lane >> 4;
;   const int srow = tid >> 2, skc = tid & 3;
;   constexpr int AROWS = MI * 32, ABYTES = AROWS * 64, STAGE = ABYTES + 16384;
;   constexpr int GRP = 4;
;   const int fr = (-(l15 >> 2)) & 3, fs = (-(srow >> 2)) & 3;
;   const int aoff = (wm * (MI * 16) + l15) * 64 + (quad ^ fr) * 16, boff = ABYTES + (wn * 64 + l15) * 64 + (quad ^ fr) * 16;
;   const int nk = K >> 5;
;   const bool a2 = (MI != 4);
;   const int a2row = (MI == 6 && tid >= 256) ? 64 : 128, a2lds = (MI == 6 && tid >= 256) ? 4096 : 8192;
;   int citem = item, ck = 0;
;   const u16* ga; const u16* gb;
;     ...
;   SETPTR(citem)
;   GLDS(0) ADV()
;   GLDS(STAGE) ADV()
;   WAITSTEP()
;   __builtin_amdgcn_s_barrier();
;   int scur = 0, snext = 2 * STAGE;
.LBB0_203:
	s_or_b64 exec, exec, s[4:5]
	s_andn2_b64 vcc, exec, s[0:1]
	s_mov_b64 s[6:7], -1
	s_barrier
	s_cbranch_vccnz .LBB0_246
	v_readlane_b32 s0, v255, 54
	s_lshr_b32 s3, s0, 1
	s_mul_i32 s0, s3, 0x1080000
	v_readlane_b32 s1, v255, 33
	v_readlane_b32 s4, v254, 17
	s_add_u32 s0, s1, s0
	v_readlane_b32 s1, v255, 34
	v_readlane_b32 s5, v254, 18
	s_addc_u32 s1, s1, 0
	s_andn2_b64 vcc, exec, s[4:5]
	s_cbranch_vccnz .LBB0_213
	v_mov_b32 v8, v200
	v_readlane_b32 s4, v254, 19
	v_ashrrev_i32_e32 v131, 2, v8
	v_lshrrev_b32_e32 v0, 4, v8
	v_sub_u32_e32 v2, 0, v0
	v_add_u32_e32 v0, s4, v131
	v_ashrrev_i32_e32 v1, 31, v0
	v_readlane_b32 s6, v254, 11
	v_xor_b32_e32 v2, v8, v2
	v_lshlrev_b64 v[0:1], 11, v[0:1]
	v_readlane_b32 s7, v254, 12
	v_lshlrev_b32_e32 v2, 4, v2
	v_readlane_b32 s4, v254, 20
	v_lshl_add_u32 v142, v8, 4, 0
	v_lshl_add_u64 v[0:1], s[6:7], 0, v[0:1]
	v_and_b32_e32 v128, 48, v2
	v_add_u32_e32 v2, s4, v131
	v_readfirstlane_b32 s4, v142
	v_readfirstlane_b32 s100, v142
	v_add_u32_e32 v6, 0x2000, v142
	v_lshl_add_u64 v[0:1], v[0:1], 0, v[128:129]
	s_mov_b32 m0, s4
	v_readfirstlane_b32 s4, v6
	v_ashrrev_i32_e32 v3, 31, v2
	global_load_lds_dwordx4 v[0:1], off
	v_lshl_add_u64 v[4:5], v[0:1], 0, s[50:51]
	s_mov_b32 m0, s4
	v_lshlrev_b64 v[2:3], 11, v[2:3]
	global_load_lds_dwordx4 v[4:5], off
	v_add_u32_e32 v4, 0x4000, v142
	v_lshl_add_u64 v[2:3], s[0:1], 0, v[2:3]
	v_readfirstlane_b32 s4, v4
	v_add_u32_e32 v6, 0x6000, v142
	v_lshl_add_u64 v[2:3], v[2:3], 0, v[128:129]
	s_mov_b32 m0, s4
	v_readfirstlane_b32 s4, v6
	v_add_u32_e32 v9, 0x8000, v142
	global_load_lds_dwordx4 v[2:3], off
	v_lshl_add_u64 v[4:5], v[2:3], 0, s[50:51]
	s_mov_b32 m0, s4
	v_readfirstlane_b32 s4, v9
	v_add_u32_e32 v9, 0xa000, v142
	global_load_lds_dwordx4 v[4:5], off
	v_lshl_add_u64 v[6:7], v[0:1], 0, 64
	s_mov_b32 m0, s4
	s_mov_b64 s[8:9], 0x40040
	v_readfirstlane_b32 s4, v9
	global_load_lds_dwordx4 v[6:7], off
	v_lshl_add_u64 v[6:7], v[0:1], 0, s[8:9]
	s_mov_b32 m0, s4
	v_lshl_add_u64 v[4:5], v[2:3], 0, 64
	global_load_lds_dwordx4 v[6:7], off
	v_add_u32_e32 v6, 0xc000, v142
	s_mov_b32 s5, 0x3ffff80
	v_readfirstlane_b32 s4, v6
	v_add_u32_e32 v6, 0xe000, v142
	s_mov_b32 m0, s4
	v_readfirstlane_b32 s4, v6
	global_load_lds_dwordx4 v[4:5], off
	v_lshl_add_u64 v[4:5], v[2:3], 0, s[8:9]
	s_mov_b32 m0, s4
	s_mov_b64 s[8:9], 0x80
	global_load_lds_dwordx4 v[4:5], off
	v_and_b32_e32 v4, 15, v8
	v_lshrrev_b32_e32 v5, 1, v8
	v_and_or_b32 v4, v5, s5, v4
	v_lshlrev_b32_e32 v143, 6, v4
	v_lshlrev_b32_e32 v4, 2, v8
	v_and_b32_e32 v4, 48, v4
	v_sub_u32_e32 v4, 0, v4
	s_waitcnt vmcnt(0)
	v_bitop3_b32 v144, v8, 48, v4 bitop3:0x48
	v_lshlrev_b32_e32 v4, 6, v8
	v_lshl_add_u64 v[132:133], s[6:7], 0, v[128:129]
	v_readlane_b32 s7, v255, 12
	s_mov_b32 s4, 0
	v_and_b32_e32 v145, 0x33c0, v4
	v_lshl_add_u64 v[138:139], v[2:3], 0, s[8:9]
	v_lshl_add_u64 v[136:137], v[0:1], 0, s[8:9]
	v_lshl_add_u64 v[134:135], s[0:1], 0, v[128:129]
	s_mov_b32 s8, 64
	s_mov_b32 s5, 0x10000
	s_mov_b32 s6, s7
	s_barrier
	s_branch .LBB0_207

; #define MFMA(a, b, c) __builtin_amdgcn_mfma_f32_16x16x32_bf16((a), (b), (c), 0, 0, 0)
; #define ADV() { ga += 32; gb += 32; ck += 32; if (ck == K) { ck = 0; citem += gridDim.x; const int ci_ = citem < total ? citem : total - 1; SETPTR(ci_) } }
; #define WAITSTEP() { if (a2) WAITV(4); else WAITV(3); }
;     ...
;     for (int kt = 0; kt < nk; ++kt) {
;       if (VAR != 1) { const char* base = lds + scur; bf16x8 a[MI], b[4];
; #pragma unroll
;         for (int i = 0; i < 4; ++i) b[i] = *(const bf16x8*)(base + boff + i * 1024);
; #pragma unroll
;         for (int i = 0; i < MI; ++i) a[i] = *(const bf16x8*)(base + aoff + i * 1024);
; #pragma unroll
;         for (int i = 0; i < MI; ++i)
; #pragma unroll
;           for (int j = 0; j < 4; ++j) acc[i][j] = MFMA(a[i], b[j], acc[i][j]);
;         if (VAR != 2) GLDS(snext)
;     ...
;         if (MI == 8) {
;           __builtin_amdgcn_sched_group_barrier(0x100, MI + 4, 0);
; #pragma unroll
;           for (int g = 0; g < 4; ++g) { __builtin_amdgcn_sched_group_barrier(0x008, 7, 0); __builtin_amdgcn_sched_group_barrier(0x010, 1, 0); }
;           __builtin_amdgcn_sched_group_barrier(0x008, 4, 0);
;         } else if (MI == 6) {
;           __builtin_amdgcn_sched_group_barrier(0x100, MI + 4, 0);
; #pragma unroll
;           for (int g = 0; g < 4; ++g) { __builtin_amdgcn_sched_group_barrier(0x008, 5, 0); __builtin_amdgcn_sched_group_barrier(0x010, 1, 0); }
;           __builtin_amdgcn_sched_group_barrier(0x008, 4, 0);
;         }
;     ...
;       }
;       ADV()
;       if (VAR == 2) {} else WAITSTEP()
;       __builtin_amdgcn_s_barrier();
;       scur = (scur == 2 * STAGE) ? 0 : scur + STAGE;
;       snext = (snext == 2 * STAGE) ? 0 : snext + STAGE;
.LBB0_209:
	s_xor_b32 s4, s4, 0x10000
	s_xor_b32 s5, s5, 0x10000
	s_waitcnt vmcnt(0)
	s_add_i32 s9, s9, -2
	s_cmp_eq_u32 s9, 0
	s_barrier
	s_cbranch_scc1 .LBB0_206
.LBB0_210:
	s_cmpk_ge_u32 s100, 0x1000
	s_cbranch_scc1 .Lffn8_hi
	s_add_i32 s62, s4, 0
	v_add3_u32 v140, s62, v143, v144
	v_add3_u32 v128, s62, v145, v144
	ds_read_b128 v[158:161], v140
	ds_read_b128 v[146:149], v128 offset:16384
	ds_read_b128 v[150:153], v128 offset:17408
	ds_read_b128 v[154:157], v128 offset:18432
	ds_read_b128 v[162:165], v128 offset:19456
	ds_read_b128 v[166:169], v140 offset:1024
	ds_read_b128 v[170:173], v140 offset:2048
	ds_read_b128 v[174:177], v140 offset:3072
	ds_read_b128 v[178:181], v140 offset:4096
	ds_read_b128 v[182:185], v140 offset:5120
	ds_read_b128 v[186:189], v140 offset:6144
	ds_read_b128 v[190:193], v140 offset:7168
	s_add_i32 s62, s5, s100
	s_mov_b32 m0, s62
	v_lshl_add_u64 v[194:195], v[136:137], 0, s[50:51]
	v_lshl_add_u64 v[196:197], v[138:139], 0, s[50:51]
	v_lshl_add_u64 v[244:245], v[136:137], 0, 64
	v_lshl_add_u64 v[246:247], v[194:195], 0, 64
	v_lshl_add_u64 v[248:249], v[138:139], 0, 64
	v_lshl_add_u64 v[250:251], v[196:197], 0, 64
	s_nop 0
	global_load_lds_dwordx4 v[136:137], off
	s_add_i32 m0, s62, 0x2000
	s_nop 0
	global_load_lds_dwordx4 v[194:195], off
	s_add_i32 m0, s62, 0x4000
	s_nop 0
	global_load_lds_dwordx4 v[138:139], off
	s_add_i32 m0, s62, 0x6000
	s_nop 0
	global_load_lds_dwordx4 v[196:197], off
	s_add_i32 m0, s62, 0x8000
	s_nop 0
	global_load_lds_dwordx4 v[244:245], off
	s_add_i32 m0, s62, 0xa000
	s_nop 0
	global_load_lds_dwordx4 v[246:247], off
	s_add_i32 m0, s62, 0xc000
	s_nop 0
	global_load_lds_dwordx4 v[248:249], off
	s_add_i32 m0, s62, 0xe000
	s_nop 0
	global_load_lds_dwordx4 v[250:251], off
	s_waitcnt lgkmcnt(10)
	v_mfma_f32_16x16x32_bf16 v[124:127], v[158:161], v[146:149], v[124:127]
	s_waitcnt lgkmcnt(9)
	v_mfma_f32_16x16x32_bf16 v[120:123], v[158:161], v[150:153], v[120:123]
	s_waitcnt lgkmcnt(8)
	v_mfma_f32_16x16x32_bf16 v[116:119], v[158:161], v[154:157], v[116:119]
	s_waitcnt lgkmcnt(7)
	v_mfma_f32_16x16x32_bf16 v[112:115], v[158:161], v[162:165], v[112:115]
	ds_read_b128 v[228:231], v128 offset:49152
	ds_read_b128 v[232:235], v128 offset:50176
	ds_read_b128 v[236:239], v128 offset:51200
	ds_read_b128 v[240:243], v128 offset:52224
	ds_read_b128 v[158:161], v140 offset:32768
	s_waitcnt lgkmcnt(11)
	v_mfma_f32_16x16x32_bf16 v[108:111], v[166:169], v[146:149], v[108:111]
	v_mfma_f32_16x16x32_bf16 v[104:107], v[166:169], v[150:153], v[104:107]
	v_mfma_f32_16x16x32_bf16 v[100:103], v[166:169], v[154:157], v[100:103]
	v_mfma_f32_16x16x32_bf16 v[96:99], v[166:169], v[162:165], v[96:99]
	ds_read_b128 v[166:169], v140 offset:33792
	s_waitcnt lgkmcnt(11)
	v_mfma_f32_16x16x32_bf16 v[92:95], v[170:173], v[146:149], v[92:95]
	v_mfma_f32_16x16x32_bf16 v[88:91], v[170:173], v[150:153], v[88:91]
	v_mfma_f32_16x16x32_bf16 v[84:87], v[170:173], v[154:157], v[84:87]
	v_mfma_f32_16x16x32_bf16 v[80:83], v[170:173], v[162:165], v[80:83]
	ds_read_b128 v[170:173], v140 offset:34816
	s_waitcnt lgkmcnt(11)
	v_mfma_f32_16x16x32_bf16 v[76:79], v[174:177], v[146:149], v[76:79]
	v_mfma_f32_16x16x32_bf16 v[72:75], v[174:177], v[150:153], v[72:75]
	v_mfma_f32_16x16x32_bf16 v[68:71], v[174:177], v[154:157], v[68:71]
	v_mfma_f32_16x16x32_bf16 v[64:67], v[174:177], v[162:165], v[64:67]
	ds_read_b128 v[174:177], v140 offset:35840
	s_waitcnt lgkmcnt(11)
	v_mfma_f32_16x16x32_bf16 v[60:63], v[178:181], v[146:149], v[60:63]
	v_mfma_f32_16x16x32_bf16 v[56:59], v[178:181], v[150:153], v[56:59]
	v_mfma_f32_16x16x32_bf16 v[52:55], v[178:181], v[154:157], v[52:55]
	v_mfma_f32_16x16x32_bf16 v[48:51], v[178:181], v[162:165], v[48:51]
	ds_read_b128 v[178:181], v140 offset:36864
	s_waitcnt lgkmcnt(11)
	v_mfma_f32_16x16x32_bf16 v[40:43], v[182:185], v[146:149], v[40:43]
	v_mfma_f32_16x16x32_bf16 v[44:47], v[182:185], v[150:153], v[44:47]
	v_mfma_f32_16x16x32_bf16 v[32:35], v[182:185], v[154:157], v[32:35]
	v_mfma_f32_16x16x32_bf16 v[36:39], v[182:185], v[162:165], v[36:39]
	ds_read_b128 v[182:185], v140 offset:37888
	s_waitcnt lgkmcnt(11)
	v_mfma_f32_16x16x32_bf16 v[24:27], v[186:189], v[146:149], v[24:27]
	v_mfma_f32_16x16x32_bf16 v[28:31], v[186:189], v[150:153], v[28:31]
	v_mfma_f32_16x16x32_bf16 v[16:19], v[186:189], v[154:157], v[16:19]
	v_mfma_f32_16x16x32_bf16 v[20:23], v[186:189], v[162:165], v[20:23]
	ds_read_b128 v[186:189], v140 offset:38912
	s_waitcnt lgkmcnt(11)
	v_mfma_f32_16x16x32_bf16 v[8:11], v[190:193], v[146:149], v[8:11]
	v_mfma_f32_16x16x32_bf16 v[12:15], v[190:193], v[150:153], v[12:15]
	v_mfma_f32_16x16x32_bf16 v[0:3], v[190:193], v[154:157], v[0:3]
	v_mfma_f32_16x16x32_bf16 v[4:7], v[190:193], v[162:165], v[4:7]
	ds_read_b128 v[190:193], v140 offset:39936
	s_waitcnt lgkmcnt(7)
	v_mfma_f32_16x16x32_bf16 v[124:127], v[158:161], v[228:231], v[124:127]
	v_mfma_f32_16x16x32_bf16 v[120:123], v[158:161], v[232:235], v[120:123]
	v_mfma_f32_16x16x32_bf16 v[116:119], v[158:161], v[236:239], v[116:119]
	v_mfma_f32_16x16x32_bf16 v[112:115], v[158:161], v[240:243], v[112:115]
	s_waitcnt lgkmcnt(6)
	v_mfma_f32_16x16x32_bf16 v[108:111], v[166:169], v[228:231], v[108:111]
	v_mfma_f32_16x16x32_bf16 v[104:107], v[166:169], v[232:235], v[104:107]
	v_mfma_f32_16x16x32_bf16 v[100:103], v[166:169], v[236:239], v[100:103]
	v_mfma_f32_16x16x32_bf16 v[96:99], v[166:169], v[240:243], v[96:99]
	s_waitcnt lgkmcnt(5)
	v_mfma_f32_16x16x32_bf16 v[92:95], v[170:173], v[228:231], v[92:95]
	v_mfma_f32_16x16x32_bf16 v[88:91], v[170:173], v[232:235], v[88:91]
	v_mfma_f32_16x16x32_bf16 v[84:87], v[170:173], v[236:239], v[84:87]
	v_mfma_f32_16x16x32_bf16 v[80:83], v[170:173], v[240:243], v[80:83]
	s_waitcnt lgkmcnt(4)
; #define MFMA(a, b, c) __builtin_amdgcn_mfma_f32_16x16x32_bf16((a), (b), (c), 0, 0, 0)
; #define ADV() { ga += 32; gb += 32; ck += 32; if (ck == K) { ck = 0; citem += gridDim.x; const int ci_ = citem < total ? citem : total - 1; SETPTR(ci_) } }
; #define WAITSTEP() { if (a2) WAITV(4); else WAITV(3); }
;     ...
;     for (int kt = 0; kt < nk; ++kt) {
;       if (VAR != 1) { const char* base = lds + scur; bf16x8 a[MI], b[4];
; #pragma unroll
;         for (int i = 0; i < 4; ++i) b[i] = *(const bf16x8*)(base + boff + i * 1024);
; #pragma unroll
;         for (int i = 0; i < MI; ++i) a[i] = *(const bf16x8*)(base + aoff + i * 1024);
; #pragma unroll
;         for (int i = 0; i < MI; ++i)
; #pragma unroll
;           for (int j = 0; j < 4; ++j) acc[i][j] = MFMA(a[i], b[j], acc[i][j]);
;         if (VAR != 2) GLDS(snext)
;     ...
;         if (MI == 8) {
;           __builtin_amdgcn_sched_group_barrier(0x100, MI + 4, 0);
; #pragma unroll
;           for (int g = 0; g < 4; ++g) { __builtin_amdgcn_sched_group_barrier(0x008, 7, 0); __builtin_amdgcn_sched_group_barrier(0x010, 1, 0); }
;           __builtin_amdgcn_sched_group_barrier(0x008, 4, 0);
;         } else if (MI == 6) {
;           __builtin_amdgcn_sched_group_barrier(0x100, MI + 4, 0);
; #pragma unroll
;           for (int g = 0; g < 4; ++g) { __builtin_amdgcn_sched_group_barrier(0x008, 5, 0); __builtin_amdgcn_sched_group_barrier(0x010, 1, 0); }
;           __builtin_amdgcn_sched_group_barrier(0x008, 4, 0);
;         }
;     ...
;       }
;       ADV()
;       if (VAR == 2) {} else WAITSTEP()
;       __builtin_amdgcn_s_barrier();
	v_mfma_f32_16x16x32_bf16 v[76:79], v[174:177], v[228:231], v[76:79]
	v_mfma_f32_16x16x32_bf16 v[72:75], v[174:177], v[232:235], v[72:75]
	v_mfma_f32_16x16x32_bf16 v[68:71], v[174:177], v[236:239], v[68:71]
	v_mfma_f32_16x16x32_bf16 v[64:67], v[174:177], v[240:243], v[64:67]
	s_waitcnt lgkmcnt(3)
	v_mfma_f32_16x16x32_bf16 v[60:63], v[178:181], v[228:231], v[60:63]
	v_mfma_f32_16x16x32_bf16 v[56:59], v[178:181], v[232:235], v[56:59]
	v_mfma_f32_16x16x32_bf16 v[52:55], v[178:181], v[236:239], v[52:55]
	v_mfma_f32_16x16x32_bf16 v[48:51], v[178:181], v[240:243], v[48:51]
	s_waitcnt lgkmcnt(2)
	v_mfma_f32_16x16x32_bf16 v[40:43], v[182:185], v[228:231], v[40:43]
	v_mfma_f32_16x16x32_bf16 v[44:47], v[182:185], v[232:235], v[44:47]
	v_mfma_f32_16x16x32_bf16 v[32:35], v[182:185], v[236:239], v[32:35]
	v_mfma_f32_16x16x32_bf16 v[36:39], v[182:185], v[240:243], v[36:39]
	s_waitcnt lgkmcnt(1)
	v_mfma_f32_16x16x32_bf16 v[24:27], v[186:189], v[228:231], v[24:27]
	v_mfma_f32_16x16x32_bf16 v[28:31], v[186:189], v[232:235], v[28:31]
	v_mfma_f32_16x16x32_bf16 v[16:19], v[186:189], v[236:239], v[16:19]
	v_mfma_f32_16x16x32_bf16 v[20:23], v[186:189], v[240:243], v[20:23]
	s_waitcnt lgkmcnt(0)
	v_mfma_f32_16x16x32_bf16 v[8:11], v[190:193], v[228:231], v[8:11]
	v_mfma_f32_16x16x32_bf16 v[12:15], v[190:193], v[232:235], v[12:15]
	v_mfma_f32_16x16x32_bf16 v[0:3], v[190:193], v[236:239], v[0:3]
	v_mfma_f32_16x16x32_bf16 v[4:7], v[190:193], v[240:243], v[4:7]
	s_add_i32 s8, s8, 64
	s_cmpk_lg_i32 s8, 0x400
	s_cbranch_scc0 .LBB0_208
	s_branch .Lffn8_adv
.Lffn8_hi:
	s_add_i32 s62, s4, 0
	v_add3_u32 v140, s62, v143, v144
	v_add3_u32 v128, s62, v145, v144
	ds_read_b128 v[158:161], v140
	ds_read_b128 v[146:149], v128 offset:16384
	ds_read_b128 v[150:153], v128 offset:17408
	ds_read_b128 v[154:157], v128 offset:18432
	ds_read_b128 v[162:165], v128 offset:19456
	ds_read_b128 v[166:169], v140 offset:1024
	ds_read_b128 v[170:173], v140 offset:2048
	ds_read_b128 v[174:177], v140 offset:3072
	ds_read_b128 v[178:181], v140 offset:4096
	ds_read_b128 v[182:185], v140 offset:5120
	ds_read_b128 v[186:189], v140 offset:6144
	ds_read_b128 v[190:193], v140 offset:7168
	s_waitcnt lgkmcnt(10)
	v_mfma_f32_16x16x32_bf16 v[124:127], v[158:161], v[146:149], v[124:127]
	s_waitcnt lgkmcnt(9)
	v_mfma_f32_16x16x32_bf16 v[120:123], v[158:161], v[150:153], v[120:123]
	s_add_i32 s62, s5, s100
	s_mov_b32 m0, s62
	v_lshl_add_u64 v[194:195], v[136:137], 0, s[50:51]
	v_lshl_add_u64 v[196:197], v[138:139], 0, s[50:51]
	v_lshl_add_u64 v[244:245], v[136:137], 0, 64
	v_lshl_add_u64 v[246:247], v[194:195], 0, 64
	v_lshl_add_u64 v[248:249], v[138:139], 0, 64
	v_lshl_add_u64 v[250:251], v[196:197], 0, 64
	s_waitcnt lgkmcnt(8)
	v_mfma_f32_16x16x32_bf16 v[116:119], v[158:161], v[154:157], v[116:119]
	s_waitcnt lgkmcnt(7)
	v_mfma_f32_16x16x32_bf16 v[112:115], v[158:161], v[162:165], v[112:115]
	ds_read_b128 v[228:231], v128 offset:49152
	ds_read_b128 v[232:235], v128 offset:50176
	ds_read_b128 v[236:239], v128 offset:51200
	ds_read_b128 v[240:243], v128 offset:52224
	ds_read_b128 v[158:161], v140 offset:32768
	s_waitcnt lgkmcnt(11)
	v_mfma_f32_16x16x32_bf16 v[108:111], v[166:169], v[146:149], v[108:111]
	v_mfma_f32_16x16x32_bf16 v[104:107], v[166:169], v[150:153], v[104:107]
	global_load_lds_dwordx4 v[136:137], off
	s_add_i32 m0, s62, 0x2000
	v_mfma_f32_16x16x32_bf16 v[100:103], v[166:169], v[154:157], v[100:103]
	v_mfma_f32_16x16x32_bf16 v[96:99], v[166:169], v[162:165], v[96:99]
	ds_read_b128 v[166:169], v140 offset:33792
	s_waitcnt lgkmcnt(11)
	v_mfma_f32_16x16x32_bf16 v[92:95], v[170:173], v[146:149], v[92:95]
	v_mfma_f32_16x16x32_bf16 v[88:91], v[170:173], v[150:153], v[88:91]
	global_load_lds_dwordx4 v[194:195], off
	s_add_i32 m0, s62, 0x4000
	v_mfma_f32_16x16x32_bf16 v[84:87], v[170:173], v[154:157], v[84:87]
	v_mfma_f32_16x16x32_bf16 v[80:83], v[170:173], v[162:165], v[80:83]
	ds_read_b128 v[170:173], v140 offset:34816
	s_waitcnt lgkmcnt(11)
	v_mfma_f32_16x16x32_bf16 v[76:79], v[174:177], v[146:149], v[76:79]
	v_mfma_f32_16x16x32_bf16 v[72:75], v[174:177], v[150:153], v[72:75]
	global_load_lds_dwordx4 v[138:139], off
	s_add_i32 m0, s62, 0x6000
	v_mfma_f32_16x16x32_bf16 v[68:71], v[174:177], v[154:157], v[68:71]
	v_mfma_f32_16x16x32_bf16 v[64:67], v[174:177], v[162:165], v[64:67]
	ds_read_b128 v[174:177], v140 offset:35840
	s_waitcnt lgkmcnt(11)
; #define MFMA(a, b, c) __builtin_amdgcn_mfma_f32_16x16x32_bf16((a), (b), (c), 0, 0, 0)
; #define ADV() { ga += 32; gb += 32; ck += 32; if (ck == K) { ck = 0; citem += gridDim.x; const int ci_ = citem < total ? citem : total - 1; SETPTR(ci_) } }
; #define WAITSTEP() { if (a2) WAITV(4); else WAITV(3); }
;     ...
;     for (int kt = 0; kt < nk; ++kt) {
;       if (VAR != 1) { const char* base = lds + scur; bf16x8 a[MI], b[4];
; #pragma unroll
;         for (int i = 0; i < 4; ++i) b[i] = *(const bf16x8*)(base + boff + i * 1024);
; #pragma unroll
;         for (int i = 0; i < MI; ++i) a[i] = *(const bf16x8*)(base + aoff + i * 1024);
; #pragma unroll
;         for (int i = 0; i < MI; ++i)
; #pragma unroll
;           for (int j = 0; j < 4; ++j) acc[i][j] = MFMA(a[i], b[j], acc[i][j]);
;         if (VAR != 2) GLDS(snext)
;     ...
;         if (MI == 8) {
;           __builtin_amdgcn_sched_group_barrier(0x100, MI + 4, 0);
; #pragma unroll
;           for (int g = 0; g < 4; ++g) { __builtin_amdgcn_sched_group_barrier(0x008, 7, 0); __builtin_amdgcn_sched_group_barrier(0x010, 1, 0); }
;           __builtin_amdgcn_sched_group_barrier(0x008, 4, 0);
;         } else if (MI == 6) {
;           __builtin_amdgcn_sched_group_barrier(0x100, MI + 4, 0);
; #pragma unroll
;           for (int g = 0; g < 4; ++g) { __builtin_amdgcn_sched_group_barrier(0x008, 5, 0); __builtin_amdgcn_sched_group_barrier(0x010, 1, 0); }
;           __builtin_amdgcn_sched_group_barrier(0x008, 4, 0);
;         }
;     ...
;       }
;       ADV()
;       if (VAR == 2) {} else WAITSTEP()
;       __builtin_amdgcn_s_barrier();
;       scur = (scur == 2 * STAGE) ? 0 : scur + STAGE;
;       snext = (snext == 2 * STAGE) ? 0 : snext + STAGE;
	v_mfma_f32_16x16x32_bf16 v[60:63], v[178:181], v[146:149], v[60:63]
	v_mfma_f32_16x16x32_bf16 v[56:59], v[178:181], v[150:153], v[56:59]
	global_load_lds_dwordx4 v[196:197], off
	s_add_i32 m0, s62, 0x8000
	v_mfma_f32_16x16x32_bf16 v[52:55], v[178:181], v[154:157], v[52:55]
	v_mfma_f32_16x16x32_bf16 v[48:51], v[178:181], v[162:165], v[48:51]
	ds_read_b128 v[178:181], v140 offset:36864
	s_waitcnt lgkmcnt(11)
	v_mfma_f32_16x16x32_bf16 v[40:43], v[182:185], v[146:149], v[40:43]
	v_mfma_f32_16x16x32_bf16 v[44:47], v[182:185], v[150:153], v[44:47]
	global_load_lds_dwordx4 v[244:245], off
	s_add_i32 m0, s62, 0xa000
	v_mfma_f32_16x16x32_bf16 v[32:35], v[182:185], v[154:157], v[32:35]
	v_mfma_f32_16x16x32_bf16 v[36:39], v[182:185], v[162:165], v[36:39]
	ds_read_b128 v[182:185], v140 offset:37888
	s_waitcnt lgkmcnt(11)
	v_mfma_f32_16x16x32_bf16 v[24:27], v[186:189], v[146:149], v[24:27]
	v_mfma_f32_16x16x32_bf16 v[28:31], v[186:189], v[150:153], v[28:31]
	global_load_lds_dwordx4 v[246:247], off
	s_add_i32 m0, s62, 0xc000
	v_mfma_f32_16x16x32_bf16 v[16:19], v[186:189], v[154:157], v[16:19]
	v_mfma_f32_16x16x32_bf16 v[20:23], v[186:189], v[162:165], v[20:23]
	ds_read_b128 v[186:189], v140 offset:38912
	s_waitcnt lgkmcnt(11)
	v_mfma_f32_16x16x32_bf16 v[8:11], v[190:193], v[146:149], v[8:11]
	v_mfma_f32_16x16x32_bf16 v[12:15], v[190:193], v[150:153], v[12:15]
	global_load_lds_dwordx4 v[248:249], off
	s_add_i32 m0, s62, 0xe000
	v_mfma_f32_16x16x32_bf16 v[0:3], v[190:193], v[154:157], v[0:3]
	v_mfma_f32_16x16x32_bf16 v[4:7], v[190:193], v[162:165], v[4:7]
	ds_read_b128 v[190:193], v140 offset:39936
	s_waitcnt lgkmcnt(7)
	v_mfma_f32_16x16x32_bf16 v[124:127], v[158:161], v[228:231], v[124:127]
	v_mfma_f32_16x16x32_bf16 v[120:123], v[158:161], v[232:235], v[120:123]
	global_load_lds_dwordx4 v[250:251], off
	v_mfma_f32_16x16x32_bf16 v[116:119], v[158:161], v[236:239], v[116:119]
	v_mfma_f32_16x16x32_bf16 v[112:115], v[158:161], v[240:243], v[112:115]
	s_waitcnt lgkmcnt(6)
	v_mfma_f32_16x16x32_bf16 v[108:111], v[166:169], v[228:231], v[108:111]
	v_mfma_f32_16x16x32_bf16 v[104:107], v[166:169], v[232:235], v[104:107]
	v_mfma_f32_16x16x32_bf16 v[100:103], v[166:169], v[236:239], v[100:103]
	v_mfma_f32_16x16x32_bf16 v[96:99], v[166:169], v[240:243], v[96:99]
	s_waitcnt lgkmcnt(5)
	v_mfma_f32_16x16x32_bf16 v[92:95], v[170:173], v[228:231], v[92:95]
	v_mfma_f32_16x16x32_bf16 v[88:91], v[170:173], v[232:235], v[88:91]
	v_mfma_f32_16x16x32_bf16 v[84:87], v[170:173], v[236:239], v[84:87]
	v_mfma_f32_16x16x32_bf16 v[80:83], v[170:173], v[240:243], v[80:83]
	s_waitcnt lgkmcnt(4)
	v_mfma_f32_16x16x32_bf16 v[76:79], v[174:177], v[228:231], v[76:79]
	v_mfma_f32_16x16x32_bf16 v[72:75], v[174:177], v[232:235], v[72:75]
	v_mfma_f32_16x16x32_bf16 v[68:71], v[174:177], v[236:239], v[68:71]
	v_mfma_f32_16x16x32_bf16 v[64:67], v[174:177], v[240:243], v[64:67]
	s_waitcnt lgkmcnt(3)
	v_mfma_f32_16x16x32_bf16 v[60:63], v[178:181], v[228:231], v[60:63]
	v_mfma_f32_16x16x32_bf16 v[56:59], v[178:181], v[232:235], v[56:59]
	v_mfma_f32_16x16x32_bf16 v[52:55], v[178:181], v[236:239], v[52:55]
	v_mfma_f32_16x16x32_bf16 v[48:51], v[178:181], v[240:243], v[48:51]
	s_waitcnt lgkmcnt(2)
	v_mfma_f32_16x16x32_bf16 v[40:43], v[182:185], v[228:231], v[40:43]
	v_mfma_f32_16x16x32_bf16 v[44:47], v[182:185], v[232:235], v[44:47]
	v_mfma_f32_16x16x32_bf16 v[32:35], v[182:185], v[236:239], v[32:35]
	v_mfma_f32_16x16x32_bf16 v[36:39], v[182:185], v[240:243], v[36:39]
	s_waitcnt lgkmcnt(1)
	v_mfma_f32_16x16x32_bf16 v[24:27], v[186:189], v[228:231], v[24:27]
	v_mfma_f32_16x16x32_bf16 v[28:31], v[186:189], v[232:235], v[28:31]
	v_mfma_f32_16x16x32_bf16 v[16:19], v[186:189], v[236:239], v[16:19]
	v_mfma_f32_16x16x32_bf16 v[20:23], v[186:189], v[240:243], v[20:23]
	s_waitcnt lgkmcnt(0)
	v_mfma_f32_16x16x32_bf16 v[8:11], v[190:193], v[228:231], v[8:11]
	v_mfma_f32_16x16x32_bf16 v[12:15], v[190:193], v[232:235], v[12:15]
	v_mfma_f32_16x16x32_bf16 v[0:3], v[190:193], v[236:239], v[0:3]
	v_mfma_f32_16x16x32_bf16 v[4:7], v[190:193], v[240:243], v[4:7]
	s_add_i32 s8, s8, 64
	s_cmpk_lg_i32 s8, 0x400
	s_cbranch_scc0 .LBB0_208
.Lffn8_adv:
	v_lshl_add_u64 v[136:137], v[136:137], 0, 64
	v_lshl_add_u64 v[138:139], v[138:139], 0, 64
	v_lshl_add_u64 v[136:137], v[136:137], 0, 64
	v_lshl_add_u64 v[138:139], v[138:139], 0, 64
	s_branch .LBB0_209
